# hg_scan: two 16-chunk batches per inner-loop trip with all 64 loads issued before the first batch's recurrence (second batch on a renamed register set)
# speedup vs baseline: 1.0047x; 1.0026x over previous
; #define BIDX (opaque_bid() * 2 + HALF_)
; __device__ __forceinline__ void phase_hg_scan(const Params& p) {
;   u16* __restrict__ states = (u16*)(p.ws + OFF_STATES);
;   const float* __restrict__ gdec = (const float*)(p.ws + OFF_GDEC);
;   const size_t nth = (size_t)VGRID * 256;
;   for (size_t e = (size_t)BIDX * 256 + TIDX; e < (size_t)8 * 16384; e += nth) {
;     const int bh = (int)(e >> 14), vd = (int)(e & 16383), d = vd & 127;
;     float S = 0.f;
;     for (int c0 = 0; c0 < 128; c0 += 16) {
;       float Lv[16], gv[16];
.LBB0_183:
	v_readlane_b32 s10, v252, 0
	v_mov_b32_e32 v0, v175
	s_lshl_b32 s0, s10, 1
	v_readfirstlane_b32 s11, v0
	s_ashr_i32 s1, s11, 8
	s_add_i32 s0, s1, s0
	s_ashr_i32 s1, s0, 31
	s_lshl_b64 s[0:1], s[0:1], 8
	v_mov_b64_e32 v[2:3], 0x20000
	v_cmp_lt_u64_e32 vcc, s[0:1], v[2:3]
	v_readlane_b32 s86, v255, 7
	v_mov_b32_e32 v4, v175
	v_readlane_b32 s82, v255, 6
	v_readlane_b32 s87, v255, 8
	s_cbranch_vccz .LBB0_189
	v_or_b32_sdwa v2, s0, v4 dst_sel:DWORD dst_unused:UNUSED_PAD src0_sel:DWORD src1_sel:BYTE_0
	v_mov_b32_e32 v3, s1
	s_lshl_b32 s0, s10, 9
	s_and_b32 s1, s11, 0x3f00
	v_and_b32_e32 v0, 0x7f, v4
	s_add_i32 s0, s0, s1
	v_mov_b32_e32 v5, 0xff
	v_lshlrev_b32_e32 v0, 2, v0
	s_waitcnt vmcnt(0)
	v_bitop3_b16 v28, s0, v4, v5 bitop3:0xf8
	s_mov_b64 s[0:1], 0

; __device__ __forceinline__ float bf2f(u16 h) { return __uint_as_float(((u32)h) << 16); }
; __device__ __forceinline__ void phase_hg_scan(const Params& p) {
;     ...
;     for (int c0 = 0; c0 < 128; c0 += 16) {
;       float Lv[16], gv[16];
; #pragma unroll
;       for (int i = 0; i < 16; ++i) {
;         const size_t item = (size_t)bh * 128 + c0 + i;
;         Lv[i] = bf2f(states[item * 16384 + vd]);
;         gv[i] = gdec[item * 128 + d];
;       }
.LBB0_186:
	v_lshl_add_u64 v[26:27], s[72:73], 0, v[6:7]
	v_add_co_u32_e32 v8, vcc, 0x5810000, v26
	s_waitcnt vmcnt(8)
	v_lshl_add_u64 v[30:31], s[72:73], 0, v[4:5]
	v_addc_co_u32_e32 v9, vcc, 0, v27, vcc
	s_waitcnt vmcnt(4)
	v_add_co_u32_e32 v32, vcc, 0x1e790000, v30
	global_load_ushort v44, v[8:9], off
	s_nop 0
	v_addc_co_u32_e32 v33, vcc, 0, v31, vcc
	v_add_co_u32_e32 v10, vcc, 0x5818000, v26
	s_mov_b64 s[12:13], 0x2000
	s_nop 0
	v_addc_co_u32_e32 v11, vcc, 0, v27, vcc
	v_add_co_u32_e32 v12, vcc, 0x5820000, v26
	global_load_dword v45, v[32:33], off
	global_load_dword v46, v[32:33], off offset:512
	global_load_dword v47, v[32:33], off offset:1024
	global_load_dword v48, v[32:33], off offset:1536
	global_load_dword v49, v[32:33], off offset:2048
	global_load_dword v50, v[32:33], off offset:2560
	global_load_dword v51, v[32:33], off offset:3072
	global_load_ushort v52, v[10:11], off
	v_addc_co_u32_e32 v13, vcc, 0, v27, vcc
	v_add_co_u32_e32 v16, vcc, 0x5828000, v26
	s_add_i32 s10, s10, 16
	s_nop 0
	v_addc_co_u32_e32 v17, vcc, 0, v27, vcc
	v_add_co_u32_e32 v14, vcc, 0x5830000, v26
	global_load_ushort v53, v[12:13], off
	global_load_ushort v54, v[16:17], off
	v_addc_co_u32_e32 v15, vcc, 0, v27, vcc
	v_add_co_u32_e32 v18, vcc, 0x5838000, v26
	v_lshl_add_u64 v[4:5], v[4:5], 0, s[12:13]
	s_nop 0
	v_addc_co_u32_e32 v19, vcc, 0, v27, vcc
	v_add_co_u32_e32 v20, vcc, 0x5840000, v26
	global_load_ushort v55, v[14:15], off
	global_load_ushort v56, v[18:19], off
	v_addc_co_u32_e32 v21, vcc, 0, v27, vcc
	v_add_co_u32_e32 v22, vcc, 0x5848000, v26
	s_mov_b64 s[12:13], 0x80000
	s_nop 0
	v_addc_co_u32_e32 v23, vcc, 0, v27, vcc
	v_add_co_u32_e32 v24, vcc, 0x5850000, v26
	global_load_ushort v57, v[20:21], off
	global_load_ushort v58, v[22:23], off
	global_load_dword v59, v[32:33], off offset:3584
	v_addc_co_u32_e32 v25, vcc, 0, v27, vcc
	v_add_co_u32_e32 v30, vcc, 0x1e791000, v30
	global_load_ushort v60, v[24:25], off
	s_nop 0
	v_addc_co_u32_e32 v31, vcc, 0, v31, vcc
	v_add_co_u32_e32 v32, vcc, 0x5858000, v26
	global_load_dword v61, v[30:31], off
	global_load_dword v62, v[30:31], off offset:512
	global_load_dword v63, v[30:31], off offset:1024
	global_load_dword v64, v[30:31], off offset:1536
	global_load_dword v65, v[30:31], off offset:2048
	global_load_dword v66, v[30:31], off offset:2560
	global_load_dword v67, v[30:31], off offset:3072
	v_addc_co_u32_e32 v33, vcc, 0, v27, vcc
	v_add_co_u32_e32 v34, vcc, 0x5860000, v26
	v_lshl_add_u64 v[6:7], v[6:7], 0, s[12:13]
	s_nop 0
	v_addc_co_u32_e32 v35, vcc, 0, v27, vcc
	v_add_co_u32_e32 v36, vcc, 0x5868000, v26
	global_load_ushort v68, v[32:33], off
	global_load_ushort v69, v[34:35], off
	v_addc_co_u32_e32 v37, vcc, 0, v27, vcc
	v_add_co_u32_e32 v38, vcc, 0x5870000, v26
	s_cmpk_lt_u32 s10, 0x70
	s_nop 0
	v_addc_co_u32_e32 v39, vcc, 0, v27, vcc
	v_add_co_u32_e32 v40, vcc, 0x5878000, v26
	global_load_ushort v70, v[36:37], off
	global_load_ushort v71, v[38:39], off
	v_addc_co_u32_e32 v41, vcc, 0, v27, vcc
	v_add_co_u32_e32 v42, vcc, 0x5880000, v26
	global_load_ushort v72, v[40:41], off
	s_nop 0
	v_addc_co_u32_e32 v43, vcc, 0, v27, vcc
	v_add_co_u32_e32 v26, vcc, 0x5888000, v26
	global_load_ushort v73, v[42:43], off
	s_nop 0
	v_addc_co_u32_e32 v27, vcc, 0, v27, vcc
	global_load_ushort v74, v[26:27], off
	s_nop 0
	global_load_dword v30, v[30:31], off offset:3584
	v_lshl_add_u64 v[98:99], s[72:73], 0, v[6:7]
	v_add_co_u32_e32 v80, vcc, 0x5810000, v98
	v_lshl_add_u64 v[102:103], s[72:73], 0, v[4:5]
	v_addc_co_u32_e32 v81, vcc, 0, v99, vcc
	v_add_co_u32_e32 v104, vcc, 0x1e790000, v102
	global_load_ushort v116, v[80:81], off
	s_nop 0
	v_addc_co_u32_e32 v105, vcc, 0, v103, vcc
	v_add_co_u32_e32 v82, vcc, 0x5818000, v98
	s_mov_b64 s[12:13], 0x2000
	s_nop 0
	v_addc_co_u32_e32 v83, vcc, 0, v99, vcc
	v_add_co_u32_e32 v84, vcc, 0x5820000, v98
	global_load_dword v117, v[104:105], off
	global_load_dword v118, v[104:105], off offset:512
	global_load_dword v119, v[104:105], off offset:1024
	global_load_dword v120, v[104:105], off offset:1536
	global_load_dword v121, v[104:105], off offset:2048
	global_load_dword v122, v[104:105], off offset:2560
	global_load_dword v123, v[104:105], off offset:3072
	global_load_ushort v124, v[82:83], off
	v_addc_co_u32_e32 v85, vcc, 0, v99, vcc
	v_add_co_u32_e32 v88, vcc, 0x5828000, v98
	s_add_i32 s10, s10, 16
	s_nop 0
	v_addc_co_u32_e32 v89, vcc, 0, v99, vcc
	v_add_co_u32_e32 v86, vcc, 0x5830000, v98
	global_load_ushort v125, v[84:85], off
	global_load_ushort v126, v[88:89], off
	v_addc_co_u32_e32 v87, vcc, 0, v99, vcc
	v_add_co_u32_e32 v90, vcc, 0x5838000, v98
	v_lshl_add_u64 v[4:5], v[4:5], 0, s[12:13]
	s_nop 0
	v_addc_co_u32_e32 v91, vcc, 0, v99, vcc
	v_add_co_u32_e32 v92, vcc, 0x5840000, v98
	global_load_ushort v127, v[86:87], off
	global_load_ushort v128, v[90:91], off
	v_addc_co_u32_e32 v93, vcc, 0, v99, vcc
	v_add_co_u32_e32 v94, vcc, 0x5848000, v98
	s_mov_b64 s[12:13], 0x80000
	s_nop 0
	v_addc_co_u32_e32 v95, vcc, 0, v99, vcc
	v_add_co_u32_e32 v96, vcc, 0x5850000, v98
	global_load_ushort v129, v[92:93], off
	global_load_ushort v130, v[94:95], off
	global_load_dword v131, v[104:105], off offset:3584
	v_addc_co_u32_e32 v97, vcc, 0, v99, vcc
	v_add_co_u32_e32 v102, vcc, 0x1e791000, v102
	global_load_ushort v132, v[96:97], off
	s_nop 0
	v_addc_co_u32_e32 v103, vcc, 0, v103, vcc
	v_add_co_u32_e32 v104, vcc, 0x5858000, v98
	global_load_dword v133, v[102:103], off
	global_load_dword v134, v[102:103], off offset:512
	global_load_dword v135, v[102:103], off offset:1024
	global_load_dword v136, v[102:103], off offset:1536
	global_load_dword v137, v[102:103], off offset:2048
	global_load_dword v138, v[102:103], off offset:2560
	global_load_dword v139, v[102:103], off offset:3072
	v_addc_co_u32_e32 v105, vcc, 0, v99, vcc
	v_add_co_u32_e32 v106, vcc, 0x5860000, v98
	v_lshl_add_u64 v[6:7], v[6:7], 0, s[12:13]
	s_nop 0
	v_addc_co_u32_e32 v107, vcc, 0, v99, vcc
	v_add_co_u32_e32 v108, vcc, 0x5868000, v98
	global_load_ushort v140, v[104:105], off
	global_load_ushort v141, v[106:107], off
	v_addc_co_u32_e32 v109, vcc, 0, v99, vcc
	v_add_co_u32_e32 v110, vcc, 0x5870000, v98
	s_cmpk_lt_u32 s10, 0x70
	s_nop 0
	v_addc_co_u32_e32 v111, vcc, 0, v99, vcc
	v_add_co_u32_e32 v112, vcc, 0x5878000, v98
	global_load_ushort v142, v[108:109], off
	global_load_ushort v143, v[110:111], off
	v_addc_co_u32_e32 v113, vcc, 0, v99, vcc
	v_add_co_u32_e32 v114, vcc, 0x5880000, v98
	global_load_ushort v144, v[112:113], off
	s_nop 0
	v_addc_co_u32_e32 v115, vcc, 0, v99, vcc
	v_add_co_u32_e32 v98, vcc, 0x5888000, v98
	global_load_ushort v145, v[114:115], off
	s_nop 0
	v_addc_co_u32_e32 v99, vcc, 0, v99, vcc
	global_load_ushort v146, v[98:99], off
	s_nop 0
	global_load_dword v102, v[102:103], off offset:3584
	s_waitcnt vmcnt(63)
; __device__ __forceinline__ void phase_hg_scan(const Params& p) {
;     ...
; #pragma unroll
;       for (int i = 0; i < 16; ++i) {
;         const size_t item = (size_t)bh * 128 + c0 + i;
;         S = gv[i] * S + Lv[i];
;         states[item * 16384 + vd] = f2bf(S);
;       }
;     }
;   }
	v_lshlrev_b32_e32 v31, 16, v44
	s_waitcnt vmcnt(62)
	v_fmac_f32_e32 v31, v29, v45
	v_cvt_pk_bf16_f32 v44, v31, s0
	global_store_short v[8:9], v44, off
	s_waitcnt vmcnt(56)
	v_lshlrev_b32_e32 v29, 16, v52
	v_fmac_f32_e32 v29, v46, v31
	v_cvt_pk_bf16_f32 v9, v29, s0
	global_store_short v[10:11], v9, off
	s_waitcnt vmcnt(56)
	v_lshlrev_b32_e32 v45, 16, v53
	s_waitcnt vmcnt(55)
	v_lshlrev_b32_e32 v8, 16, v54
	v_fmac_f32_e32 v45, v47, v29
	v_cvt_pk_bf16_f32 v9, v45, s0
	v_fmac_f32_e32 v8, v48, v45
	global_store_short v[12:13], v9, off
	v_cvt_pk_bf16_f32 v9, v8, s0
	global_store_short v[16:17], v9, off
	s_waitcnt vmcnt(56)
	v_lshlrev_b32_e32 v29, 16, v55
	s_waitcnt vmcnt(55)
	v_lshlrev_b32_e32 v10, 16, v56
	v_fmac_f32_e32 v29, v49, v8
	v_cvt_pk_bf16_f32 v9, v29, s0
	v_fmac_f32_e32 v10, v50, v29
	global_store_short v[14:15], v9, off
	v_cvt_pk_bf16_f32 v9, v10, s0
	global_store_short v[18:19], v9, off
	s_waitcnt vmcnt(56)
	v_lshlrev_b32_e32 v8, 16, v57
	s_waitcnt vmcnt(55)
	v_lshlrev_b32_e32 v11, 16, v58
	v_fmac_f32_e32 v8, v51, v10
	v_cvt_pk_bf16_f32 v9, v8, s0
	s_waitcnt vmcnt(54)
	v_fmac_f32_e32 v11, v59, v8
	global_store_short v[20:21], v9, off
	v_cvt_pk_bf16_f32 v8, v11, s0
	s_waitcnt vmcnt(54)
	v_lshlrev_b32_e32 v10, 16, v60
	s_waitcnt vmcnt(53)
	v_fmac_f32_e32 v10, v61, v11
	global_store_short v[22:23], v8, off
	v_cvt_pk_bf16_f32 v8, v10, s0
	global_store_short v[24:25], v8, off
	s_waitcnt vmcnt(48)
	v_lshlrev_b32_e32 v9, 16, v68
	s_waitcnt vmcnt(47)
	v_lshlrev_b32_e32 v11, 16, v69
	v_fmac_f32_e32 v9, v62, v10
	v_fmac_f32_e32 v11, v63, v9
	v_cvt_pk_bf16_f32 v10, v9, s0
	global_store_short v[32:33], v10, off
	v_cvt_pk_bf16_f32 v10, v11, s0
	global_store_short v[34:35], v10, off
	s_waitcnt vmcnt(48)
	v_lshlrev_b32_e32 v8, 16, v70
	s_waitcnt vmcnt(47)
	v_lshlrev_b32_e32 v9, 16, v71
	v_fmac_f32_e32 v8, v64, v11
	v_fmac_f32_e32 v9, v65, v8
	v_cvt_pk_bf16_f32 v10, v8, s0
	global_store_short v[36:37], v10, off
	s_waitcnt vmcnt(47)
	v_lshlrev_b32_e32 v11, 16, v72
	v_fmac_f32_e32 v11, v66, v9
	v_cvt_pk_bf16_f32 v10, v9, s0
	v_cvt_pk_bf16_f32 v9, v11, s0
	global_store_short v[40:41], v9, off
	s_waitcnt vmcnt(47)
	v_lshlrev_b32_e32 v8, 16, v73
	v_fmac_f32_e32 v8, v67, v11
	s_waitcnt vmcnt(46)
	v_lshlrev_b32_e32 v29, 16, v74
	s_waitcnt vmcnt(45)
	v_fmac_f32_e32 v29, v30, v8
	v_cvt_pk_bf16_f32 v9, v8, s0
	v_cvt_pk_bf16_f32 v8, v29, s0
	global_store_short v[38:39], v10, off
	global_store_short v[42:43], v9, off
	global_store_short v[26:27], v8, off
	s_waitcnt vmcnt(47)
	v_lshlrev_b32_e32 v103, 16, v116
	s_waitcnt vmcnt(46)
	v_fmac_f32_e32 v103, v29, v117
	v_cvt_pk_bf16_f32 v116, v103, s0
	global_store_short v[80:81], v116, off
	s_waitcnt vmcnt(40)
	v_lshlrev_b32_e32 v29, 16, v124
	v_fmac_f32_e32 v29, v118, v103
	v_cvt_pk_bf16_f32 v81, v29, s0
	global_store_short v[82:83], v81, off
	s_waitcnt vmcnt(40)
	v_lshlrev_b32_e32 v117, 16, v125
	s_waitcnt vmcnt(39)
	v_lshlrev_b32_e32 v80, 16, v126
	v_fmac_f32_e32 v117, v119, v29
	v_cvt_pk_bf16_f32 v81, v117, s0
	v_fmac_f32_e32 v80, v120, v117
	global_store_short v[84:85], v81, off
	v_cvt_pk_bf16_f32 v81, v80, s0
	global_store_short v[88:89], v81, off
	s_waitcnt vmcnt(40)
	v_lshlrev_b32_e32 v29, 16, v127
	s_waitcnt vmcnt(39)
	v_lshlrev_b32_e32 v82, 16, v128
	v_fmac_f32_e32 v29, v121, v80
	v_cvt_pk_bf16_f32 v81, v29, s0
	v_fmac_f32_e32 v82, v122, v29
	global_store_short v[86:87], v81, off
	v_cvt_pk_bf16_f32 v81, v82, s0
	global_store_short v[90:91], v81, off
	s_waitcnt vmcnt(40)
	v_lshlrev_b32_e32 v80, 16, v129
	s_waitcnt vmcnt(39)
	v_lshlrev_b32_e32 v83, 16, v130
	v_fmac_f32_e32 v80, v123, v82
	v_cvt_pk_bf16_f32 v81, v80, s0
	s_waitcnt vmcnt(38)
	v_fmac_f32_e32 v83, v131, v80
	global_store_short v[92:93], v81, off
	v_cvt_pk_bf16_f32 v80, v83, s0
	s_waitcnt vmcnt(38)
	v_lshlrev_b32_e32 v82, 16, v132
	s_waitcnt vmcnt(37)
	v_fmac_f32_e32 v82, v133, v83
	global_store_short v[94:95], v80, off
	v_cvt_pk_bf16_f32 v80, v82, s0
	global_store_short v[96:97], v80, off
	s_waitcnt vmcnt(32)
	v_lshlrev_b32_e32 v81, 16, v140
	s_waitcnt vmcnt(31)
	v_lshlrev_b32_e32 v83, 16, v141
	v_fmac_f32_e32 v81, v134, v82
	v_fmac_f32_e32 v83, v135, v81
	v_cvt_pk_bf16_f32 v82, v81, s0
	global_store_short v[104:105], v82, off
	v_cvt_pk_bf16_f32 v82, v83, s0
	global_store_short v[106:107], v82, off
	s_waitcnt vmcnt(32)
	v_lshlrev_b32_e32 v80, 16, v142
	s_waitcnt vmcnt(31)
	v_lshlrev_b32_e32 v81, 16, v143
	v_fmac_f32_e32 v80, v136, v83
	v_fmac_f32_e32 v81, v137, v80
	v_cvt_pk_bf16_f32 v82, v80, s0
	global_store_short v[108:109], v82, off
	s_waitcnt vmcnt(31)
	v_lshlrev_b32_e32 v83, 16, v144
	v_fmac_f32_e32 v83, v138, v81
	v_cvt_pk_bf16_f32 v82, v81, s0
	v_cvt_pk_bf16_f32 v81, v83, s0
	global_store_short v[112:113], v81, off
	s_waitcnt vmcnt(31)
	v_lshlrev_b32_e32 v80, 16, v145
	v_fmac_f32_e32 v80, v139, v83
	s_waitcnt vmcnt(30)
	v_lshlrev_b32_e32 v29, 16, v146
	s_waitcnt vmcnt(29)
	v_fmac_f32_e32 v29, v102, v80
	v_cvt_pk_bf16_f32 v81, v80, s0
	v_cvt_pk_bf16_f32 v80, v29, s0
	global_store_short v[110:111], v82, off
	global_store_short v[114:115], v81, off
	global_store_short v[98:99], v80, off
	s_cbranch_scc1 .LBB0_186
	v_lshl_add_u64 v[2:3], v[2:3], 0, s[60:61]
	s_mov_b64 s[10:11], 0x1ffff
	v_cmp_lt_u64_e32 vcc, s[10:11], v[2:3]
	v_readlane_b32 s10, v254, 35
	s_or_b64 s[0:1], vcc, s[0:1]
	s_nop 0
	v_add_u16_e32 v28, s10, v28
	s_andn2_b64 exec, exec, s[0:1]
	s_cbranch_execnz .LBB0_185
	s_or_b64 exec, exec, s[0:1]
